# SWA units: sink logit loaded at unit start + next-unit prefetch (K/V pair, Q); all four attention unit types now prefetch their successor
# speedup vs baseline: 1.0167x; 1.0040x over previous
.LBB0_276:
	s_or_b64 exec, exec, s[4:5]
	s_cmpk_gt_i32 s37, 0x3ff
	s_mov_b64 s[4:5], -1
	s_cbranch_scc0 .LBB0_288
	s_add_i32 s4, s37, 0xfffffc00
	s_lshr_b32 s4, s4, 5
	v_mov_b32_e32 v0, v216
	s_sub_i32 s29, 31, s4
	s_lshl_b32 s5, s37, 1
	v_readfirstlane_b32 s4, v0
	s_ashr_i32 s34, s4, 6
	s_ashr_i32 s36, s4, 8
	s_lshl_b32 s4, s37, 10
	s_and_b32 s5, s5, 6
	s_and_b32 s42, s4, 0x7000
	s_and_b32 s4, s34, 3
	s_add_i32 s28, s36, s5
	v_readlane_b32 vcc_lo, v253, 24
	v_readlane_b32 vcc_hi, v253, 25
	s_lshl_b32 s12, s28, 2
	s_add_u32 vcc_lo, vcc_lo, s12
	s_addc_u32 vcc_hi, vcc_hi, 0
	global_load_dword v190, v193, vcc
	s_lshl_b32 s5, s29, 7
	s_lshl_b32 s8, s4, 5
	s_or_b32 s5, s8, s5
	s_lshl_b32 s8, s28, 6
	v_and_b32_e32 v1, 31, v0
	s_ashr_i32 s9, s8, 31
	v_or_b32_e32 v3, s5, v1
	s_lshl_b64 s[12:13], s[8:9], 1
	v_readlane_b32 s5, v255, 14
	s_add_u32 s12, s5, s12
	v_readlane_b32 s5, v255, 15
	s_addc_u32 s13, s5, s13
	s_lshl_b32 s5, s28, 4
	s_and_b32 s18, s5, 0xffffffc0
	s_ashr_i32 s19, s18, 31
	v_and_b32_e32 v4, 63, v0
	s_lshl_b64 s[18:19], s[18:19], 1
	v_readlane_b32 s5, v255, 16
	s_add_u32 s20, s5, s18
	v_readlane_b32 s5, v255, 17
	v_or_b32_e32 v4, s42, v4
	s_addc_u32 s21, s5, s19
	v_readlane_b32 s5, v255, 18
	v_mul_u32_u24_e32 v4, 0x600, v4
	s_add_u32 s38, s5, s18
	v_readlane_b32 s5, v255, 19
	v_lshlrev_b32_e32 v192, 1, v4
	s_addc_u32 s39, s5, s19
	v_lshl_add_u64 v[4:5], s[20:21], 0, v[192:193]
	s_lshl_b32 s20, s34, 3
	s_ashr_i32 s21, s20, 31
	v_lshl_add_u64 v[128:129], s[20:21], 1, v[4:5]
	v_bfe_u32 v4, v0, 2, 4
	v_lshl_or_b32 v4, s4, 4, v4
	v_or_b32_e32 v4, s42, v4
	v_mul_u32_u24_e32 v4, 0x600, v4
	v_lshlrev_b32_e32 v192, 1, v4
	s_lshl_b32 s20, s36, 5
	v_lshl_add_u64 v[4:5], s[38:39], 0, v[192:193]
	s_ashr_i32 s21, s20, 31
	v_lshl_add_u64 v[6:7], s[20:21], 1, v[4:5]
	v_lshlrev_b32_e32 v4, 3, v0
	s_lshl_b32 s5, s29, 1
	v_and_b32_e32 v4, 24, v4
	v_sub_u32_e64 v140, s5, 2 clamp
	v_lshlrev_b32_e32 v192, 1, v4
	s_mov_b32 s14, 0x30000
	v_lshl_add_u64 v[130:131], v[6:7], 0, v[192:193]
	v_mad_u64_u32 v[6:7], s[20:21], v140, s14, v[128:129]
	s_lshl_b32 s19, s34, 10
	s_add_i32 s19, s19, 0
	s_cmp_lg_u32 s32, 0
	s_cbranch_scc1 .Lpf1_s0
	s_mov_b32 s20, m0
	s_mov_b32 m0, s19
	s_nop 0
	global_load_lds_dwordx4 v[6:7], off
	s_mov_b32 m0, s20
.Lpf1_s0:
	s_max_u32 s18, s5, 2
	v_mad_u64_u32 v[6:7], s[20:21], v140, s14, v[130:131]
	s_lshl_b32 s20, s36, 12
	s_lshl_b32 s21, s4, 10
	s_or_b32 s20, s21, s20
	s_add_i32 s21, s20, 0
	s_add_i32 s20, s21, 0xc000
	s_cmp_lg_u32 s32, 0
	s_cbranch_scc1 .Lpf1_s1
	s_mov_b32 s29, m0
	s_mov_b32 m0, s20
	s_nop 0
	global_load_lds_dwordx4 v[6:7], off
	s_mov_b32 m0, s29
.Lpf1_s1:
	s_add_i32 s29, s18, -1
	v_mad_u64_u32 v[6:7], s[38:39], s29, v230, v[128:129]
	s_add_i32 s34, s19, 0x3000
	s_cmp_lg_u32 s32, 0
	s_cbranch_scc1 .Lpf1_s2
	s_mov_b32 s36, m0
	s_mov_b32 m0, s34
	s_nop 0
	global_load_lds_dwordx4 v[6:7], off
	s_mov_b32 m0, s36
.Lpf1_s2:
	v_mad_u64_u32 v[6:7], s[38:39], s29, v230, v[130:131]
	v_bfe_u32 v2, v0, 5, 1
	s_add_i32 s21, s21, 0xe000
	s_cmp_lg_u32 s32, 0
	s_cbranch_scc1 .Lpf1_s3
	s_mov_b32 s29, m0
	s_mov_b32 m0, s21
	s_nop 0
	global_load_lds_dwordx4 v[6:7], off
	s_mov_b32 m0, s29
.Lpf1_s3:
	v_or_b32_e32 v137, s42, v3
	v_mov_b64_e32 v[6:7], s[12:13]
	s_movk_i32 s12, 0xc00
	v_mad_u64_u32 v[6:7], s[12:13], v137, s12, v[6:7]
	v_lshlrev_b32_e32 v192, 4, v2
	v_lshl_add_u64 v[6:7], v[6:7], 0, v[192:193]
	s_cmp_lg_u32 s32, 0
	s_cbranch_scc1 .Lpf1_q1
	global_load_dwordx4 v[80:83], v[6:7], off
	global_load_dwordx4 v[84:87], v[6:7], off offset:32
	global_load_dwordx4 v[88:91], v[6:7], off offset:64
	global_load_dwordx4 v[92:95], v[6:7], off offset:96
	s_branch .Lpf1_q2
.Lpf1_q1:
	v_mov_b32_e32 v80, v174
	v_mov_b32_e32 v81, v175
	v_mov_b32_e32 v82, v176
	v_mov_b32_e32 v83, v177
	v_mov_b32_e32 v84, v178
	v_mov_b32_e32 v85, v179
	v_mov_b32_e32 v86, v180
	v_mov_b32_e32 v87, v181
	v_mov_b32_e32 v88, v182
	v_mov_b32_e32 v89, v183
	v_mov_b32_e32 v90, v184
	v_mov_b32_e32 v91, v185
	v_mov_b32_e32 v92, v186
	v_mov_b32_e32 v93, v187
	v_mov_b32_e32 v94, v188
	v_mov_b32_e32 v95, v189
.Lpf1_q2:
	v_mov_b32_e32 v32, 0
	v_mov_b32_e32 v5, 0
	s_sub_i32 s12, s5, s18
	s_add_i32 s12, s12, 4
	s_ashr_i32 s21, s12, 1
	v_mov_b32_e32 v141, 0
	v_lshlrev_b32_e32 v136, 2, v2
	s_cmp_lt_i32 s21, 1
	s_cmp_lg_u32 s32, 0
	s_cbranch_scc1 .Lpf1_w3
	s_waitcnt vmcnt(3)

.Lpf1_w1:
	s_cmp_lg_u32 s32, 0
	s_cbranch_scc1 .Lpf1_w0
	s_waitcnt vmcnt(0)
.Lpf1_w0:
	s_cmp_lg_u32 s32, 0
	s_cbranch_scc1 .Lpf1_wb
	s_waitcnt vmcnt(0)
.Lpf1_wb:
	s_mov_b32 s32, 0
	s_waitcnt lgkmcnt(0)
	s_barrier
	s_cmp_lt_i32 s21, 1
	s_cbranch_scc1 .LBB0_289
	s_add_i32 s12, s28, 1
	v_cvt_f32_i32_e32 v5, s12
	v_cvt_f32_u32_e32 v142, v3
	s_lshr_b32 s4, s4, 1
	v_lshlrev_b32_e32 v1, 4, v1
	v_exp_f32_e64 v3, -v5
	v_lshlrev_b32_e32 v2, 10, v2
	v_mov_b32_e32 v192, v193
	s_or_b32 s29, s4, s5
	v_mul_f32_e32 v132, 0x3fb8aa3b, v3
	v_lshlrev_b32_e32 v3, 1, v0
	v_lshrrev_b32_e32 v0, 2, v0
	v_and_or_b32 v0, v0, 3, v136
	v_and_b32_e32 v3, 32, v3
	v_lshl_add_u32 v0, v0, 6, 0
	v_add3_u32 v145, 0, v2, v1
	v_add3_u32 v147, v0, v3, v4
	v_mov_b32_e32 v194, v193
	v_mov_b32_e32 v195, v193
	v_mov_b32_e32 v196, v193
	v_mov_b32_e32 v197, v193
	v_mov_b32_e32 v198, v193
	v_mov_b32_e32 v199, v193
	v_mov_b32_e32 v200, v193
	v_mov_b32_e32 v201, v193
	v_mov_b32_e32 v202, v193
	v_mov_b32_e32 v203, v193
	v_mov_b32_e32 v204, v193
	v_mov_b32_e32 v205, v193
	v_mov_b32_e32 v206, v193
	v_mov_b32_e32 v207, v193
	v_mov_b64_e32 v[16:17], v[192:193]
	v_mov_b64_e32 v[0:1], v[192:193]
	v_mov_b32_e32 v33, v32
	v_mov_b32_e32 v34, v32
	v_sub_u32_e64 v144, s29, 2 clamp
	v_mov_b32_e32 v35, v32
	v_mov_b32_e32 v36, v32
	v_mov_b32_e32 v37, v32
	v_mov_b32_e32 v38, v32
	v_mov_b32_e32 v39, v32
	v_mov_b32_e32 v40, v32
	v_mov_b32_e32 v41, v32
	v_mov_b32_e32 v42, v32
	v_mov_b32_e32 v43, v32
	v_mov_b32_e32 v44, v32
	v_mov_b32_e32 v45, v32
	v_mov_b32_e32 v46, v32
	v_mov_b32_e32 v47, v32
	s_or_b32 s34, s18, 1
	v_mov_b32_e32 v133, v132
	s_mov_b32 s36, 0
	v_mov_b32_e32 v143, 0
	v_mov_b64_e32 v[18:19], v[194:195]
	v_mov_b64_e32 v[20:21], v[196:197]
	v_mov_b64_e32 v[22:23], v[198:199]
	v_mov_b64_e32 v[24:25], v[200:201]
	v_mov_b64_e32 v[26:27], v[202:203]
	v_mov_b64_e32 v[28:29], v[204:205]
	v_mov_b64_e32 v[30:31], v[206:207]
	v_mov_b64_e32 v[2:3], v[194:195]
	v_mov_b64_e32 v[4:5], v[196:197]
	v_mov_b64_e32 v[6:7], v[198:199]
	v_mov_b64_e32 v[8:9], v[200:201]
	v_mov_b64_e32 v[10:11], v[202:203]
	v_mov_b64_e32 v[12:13], v[204:205]
	v_mov_b64_e32 v[14:15], v[206:207]
	v_mov_b32_e32 v141, 0
	s_branch .LBB0_280
.Lpf1_block:
	s_cmp_lg_u32 s42, 2
	s_cbranch_scc1 .LBB0_282
	s_xor_b32 s5, s44, 1
	s_lshl_b32 s5, s5, 2
	s_add_i32 s5, s5, 0x15500
	v_mov_b32_e32 v48, s5
	ds_read_b32 v48, v48
	s_waitcnt lgkmcnt(0)
	v_readfirstlane_b32 s5, v48
	s_sub_i32 s5, s5, 0x400
	s_cmp_lt_u32 s5, 0x400
	s_cbranch_scc0 .LBB0_282
	s_mov_b32 s32, 1
	s_lshr_b32 s12, s5, 5
	s_sub_i32 s12, 31, s12
	s_lshr_b32 s13, s5, 2
	s_and_b32 s13, s13, 7
	s_and_b32 s5, s5, 3
	s_lshl_b32 s38, s12, 1
	s_sub_i32 s38, s38, 2
	s_max_i32 s38, s38, 0
	s_lshr_b32 s39, s5, 1
	s_lshl_b32 s39, s39, 7
	s_mul_i32 s43, s13, 0xc00000
	s_add_u32 s39, s39, s43
	s_mul_i32 s38, s38, 0x30000
	s_add_u32 s39, s39, s38
	v_readlane_b32 vcc_lo, v255, 16
	v_readlane_b32 vcc_hi, v255, 17
	s_add_u32 vcc_lo, vcc_lo, s39
	s_addc_u32 vcc_hi, vcc_hi, 0
	v_and_b32_e32 v50, 63, v216
	v_lshrrev_b32_e32 v49, 6, v216
	v_mul_u32_u24_e32 v48, 0xc00, v50
	v_lshl_or_b32 v48, v49, 4, v48
	s_mov_b32 m0, s19
	s_nop 0
	global_load_lds_dwordx4 v48, vcc
	s_add_u32 vcc_lo, vcc_lo, 0x30000
	s_addc_u32 vcc_hi, vcc_hi, 0
	s_add_i32 m0, s19, 0x3000
	s_nop 0
	global_load_lds_dwordx4 v48, vcc
	v_readlane_b32 vcc_lo, v255, 18
	v_readlane_b32 vcc_hi, v255, 19
	s_add_u32 vcc_lo, vcc_lo, s39
	s_addc_u32 vcc_hi, vcc_hi, 0
	v_lshrrev_b32_e32 v51, 2, v50
	v_and_b32_e32 v52, 3, v49
	v_lshl_or_b32 v51, v52, 4, v51
	v_mul_u32_u24_e32 v51, 0xc00, v51
	v_lshrrev_b32_e32 v53, 2, v49
	v_lshl_or_b32 v51, v53, 6, v51
	v_and_b32_e32 v53, 3, v50
	v_lshl_or_b32 v51, v53, 4, v51
	s_mov_b32 m0, s20
	s_nop 0
	global_load_lds_dwordx4 v51, vcc
	s_add_u32 vcc_lo, vcc_lo, 0x30000
	s_addc_u32 vcc_hi, vcc_hi, 0
	s_add_i32 m0, s20, 0x2000
	s_nop 0
	global_load_lds_dwordx4 v51, vcc
	v_readlane_b32 vcc_lo, v255, 14
	v_readlane_b32 vcc_hi, v255, 15
	v_readfirstlane_b32 s38, v49
	s_lshr_b32 s38, s38, 2
	s_lshl_b32 s5, s5, 1
	s_add_i32 s38, s38, s5
	s_lshl_b32 s38, s38, 7
	s_lshl_b32 s13, s13, 12
	s_lshl_b32 s12, s12, 7
	s_add_i32 s13, s13, s12
	s_mul_i32 s13, s13, 0xc00
	s_add_u32 s13, s13, s38
	s_add_u32 vcc_lo, vcc_lo, s13
	s_addc_u32 vcc_hi, vcc_hi, 0
	v_and_b32_e32 v51, 31, v216
	v_lshl_or_b32 v51, v52, 5, v51
	v_mul_u32_u24_e32 v51, 0xc00, v51
	v_bfe_u32 v53, v216, 5, 1
	v_lshl_or_b32 v51, v53, 4, v51
	global_load_dwordx4 v[174:177], v51, vcc
	global_load_dwordx4 v[178:181], v51, vcc offset:32
	global_load_dwordx4 v[182:185], v51, vcc offset:64
	global_load_dwordx4 v[186:189], v51, vcc offset:96
	s_branch .LBB0_282
.LBB0_279:
	s_cmp_lg_u32 s36, 1
	s_cbranch_scc1 .Lpf1_nosu
	v_readfirstlane_b32 vcc_lo, v216
	s_cmp_lt_u32 vcc_lo, 64
	s_cbranch_scc0 .Lpf1_nosu
	s_waitcnt vmcnt(0)
	v_readfirstlane_b32 vcc_lo, v146
	s_xor_b32 vcc_hi, s44, 1
	s_lshl_b32 vcc_hi, vcc_hi, 2
	s_add_i32 vcc_hi, vcc_hi, 0x15500
	v_mov_b32_e32 v48, vcc_hi
	v_mov_b32_e32 v49, vcc_lo
	ds_write_b32 v48, v49

.LBB0_290:
	s_ashr_i32 s29, s28, 31
	s_lshl_b64 s[4:5], s[28:29], 2
	v_readlane_b32 s12, v253, 24
	v_readlane_b32 s13, v253, 25
	s_add_u32 s4, s12, s4
	s_addc_u32 s5, s13, s5
	s_waitcnt vmcnt(0)
	v_mov_b32_e32 v33, v190
	s_mov_b32 s4, 0x3fb8aa3b
	v_mov_b32_e32 v32, v141
	s_nop 1
	v_permlane32_swap_b32_e32 v141, v32
	v_add_f32_e32 v32, v141, v32
	v_lshlrev_b32_e32 v192, 11, v137
	v_fma_f32 v33, v33, s4, -v143
	v_exp_f32_e32 v33, v33
	v_readlane_b32 s4, v255, 32
	v_readlane_b32 s5, v255, 33
	v_add_f32_e32 v34, v32, v33
	s_nop 0
	v_lshl_add_u64 v[32:33], s[4:5], 0, v[192:193]
	v_lshl_add_u64 v[32:33], s[8:9], 1, v[32:33]
	s_mov_b64 s[4:5], 0x18000400
	v_lshl_add_u64 v[32:33], v[32:33], 0, s[4:5]
	s_branch .LBB0_310
